# Z units stored chunk-major (unit c*32+bh) so the 32 rwkv_apply workgroups read one contiguous span per step
# speedup vs baseline: 1.0371x; 1.0030x over previous
.LBB0_804:
	s_or_b64 exec, exec, s[10:11]
	s_waitcnt lgkmcnt(0)
	v_add_f32_e32 v203, v203, v204
	v_mul_f32_e32 v204, 0x4f800000, v203
	v_cmp_gt_f32_e32 vcc, s51, v203
	v_sub_f32_e32 v225, v226, v225
	v_mul_f32_e32 v225, 0x3fb8aa3b, v225
	v_cndmask_b32_e32 v203, v203, v204, vcc
	v_sqrt_f32_e32 v204, v203
	v_exp_f32_e32 v225, v225
	v_mul_f32_e32 v226, 0xbfb8aa3b, v226
	v_exp_f32_e32 v226, v226
	v_add_u32_e32 v227, -1, v204
	v_fma_f32 v229, -v227, v204, v203
	v_add_u32_e32 v228, 1, v204
	v_cmp_ge_f32_e64 s[20:21], 0, v229
	s_nop 1
	v_cndmask_b32_e64 v227, v204, v227, s[20:21]
	v_fma_f32 v204, -v228, v204, v203
	v_cmp_lt_f32_e64 s[20:21], 0, v204
	s_nop 1
	v_cndmask_b32_e64 v204, v227, v228, s[20:21]
	v_mul_f32_e32 v227, 0x37800000, v204
	v_cndmask_b32_e32 v204, v204, v227, vcc
	v_cmp_class_f32_e32 vcc, v203, v172
	s_nop 1
	v_cndmask_b32_e32 v203, v204, v203, vcc
	v_max_f32_e32 v203, 0x2b8cbccc, v203
	v_div_scale_f32 v204, s[10:11], v203, v203, 1.0
	v_rcp_f32_e32 v227, v204
	s_lshr_b32 s10, s29, 8
	s_lshl_b32 s11, s3, 5
	s_add_i32 s10, s10, s11
	s_mul_hi_i32 s11, s10, 0x3200
	s_mulk_i32 s10, 0x3200
	v_fma_f32 v228, -v204, v227, 1.0
	v_fmac_f32_e32 v227, v228, v227
	v_div_scale_f32 v228, vcc, 1.0, v203, 1.0
	v_mul_f32_e32 v229, v228, v227
	v_fma_f32 v230, -v204, v229, v228
	v_fmac_f32_e32 v229, v230, v227
	v_fma_f32 v204, -v204, v229, v228
	v_div_fmas_f32 v204, v204, v227, v229
	v_div_fixup_f32 v203, v204, v203, 1.0
	v_and_b32_e32 v204, 0xffff0000, v83
	v_and_b32_e32 v227, 0xffff0000, v85
	s_waitcnt vmcnt(0)
	v_and_b32_e32 v228, 0xffff0000, v87
	v_fma_f32 v227, v96, v227, -v204
	v_fmac_f32_e32 v204, v15, v227
	v_add_f32_e32 v227, -1.0, v228
	v_lshlrev_b32_e32 v83, 16, v83
	v_lshlrev_b32_e32 v85, 16, v85
	v_fma_f32 v227, v19, v227, 1.0
	v_mul_f32_e32 v199, v199, v203
	v_lshlrev_b32_e32 v87, 16, v87
	v_fma_f32 v85, v96, v85, -v83
	v_mul_f32_e32 v131, v131, v227
	v_mul_f32_e32 v225, v199, v225
	v_mul_f32_e32 v199, v199, v228
	v_fmac_f32_e32 v83, v14, v85
	v_add_f32_e32 v85, -1.0, v87
	v_mul_f32_e32 v199, v199, v226
	v_mul_f32_e32 v226, v131, v226
	v_mul_f32_e32 v131, v204, v89
	v_fma_f32 v85, v18, v85, 1.0
	v_sub_f32_e32 v89, v224, v223
	v_mul_f32_e32 v85, v130, v85
	v_mul_f32_e32 v89, 0x3fb8aa3b, v89
	v_mul_f32_e32 v130, 0xbfb8aa3b, v224
	v_exp_f32_e32 v89, v89
	v_exp_f32_e32 v130, v130
	v_mul_f32_e32 v198, v198, v203
	v_mul_f32_e32 v87, v198, v87
	v_mul_f32_e32 v204, v198, v89
	v_mul_f32_e32 v198, v87, v130
	v_mul_f32_e32 v223, v85, v130
	v_mul_f32_e32 v130, v83, v222
	v_and_b32_e32 v83, 0xffff0000, v82
	v_and_b32_e32 v85, 0xffff0000, v84
	v_and_b32_e32 v87, 0xffff0000, v86
	v_fma_f32 v85, v96, v85, -v83
	v_fmac_f32_e32 v83, v13, v85
	v_add_f32_e32 v85, -1.0, v87
	v_fma_f32 v85, v17, v85, 1.0
	v_sub_f32_e32 v89, v221, v220
	v_mul_f32_e32 v85, v135, v85
	v_mul_f32_e32 v89, 0x3fb8aa3b, v89
	v_mul_f32_e32 v135, 0xbfb8aa3b, v221
	v_exp_f32_e32 v89, v89
	v_exp_f32_e32 v135, v135
	v_mul_f32_e32 v195, v195, v203
	v_mul_f32_e32 v87, v195, v87
	v_mul_f32_e32 v220, v195, v89
	v_mul_f32_e32 v195, v87, v135
	v_mul_f32_e32 v221, v85, v135
	v_mul_f32_e32 v135, v83, v88
	v_lshlrev_b32_e32 v82, 16, v82
	v_lshlrev_b32_e32 v83, 16, v84
	v_lshlrev_b32_e32 v84, 16, v86
	v_mul_f32_e32 v86, 0xbfb8aa3b, v219
	v_fma_f32 v83, v96, v83, -v82
	v_exp_f32_e32 v86, v86
	v_fmac_f32_e32 v82, v12, v83
	v_add_f32_e32 v83, -1.0, v84
	v_fma_f32 v83, v16, v83, 1.0
	v_mul_f32_e32 v87, v194, v203
	v_mul_f32_e32 v83, v134, v83
	v_sub_f32_e32 v85, v219, v218
	v_mul_f32_e32 v84, v87, v84
	v_mul_f32_e32 v85, 0x3fb8aa3b, v85
	v_mul_f32_e32 v218, v84, v86
	v_mul_f32_e32 v219, v83, v86
	v_mul_f32_e32 v134, v82, v217
	v_and_b32_e32 v82, 0xffff0000, v75
	v_and_b32_e32 v83, 0xffff0000, v77
	v_mul_f32_e32 v86, 0xbfb8aa3b, v216
	v_exp_f32_e32 v85, v85
	v_and_b32_e32 v84, 0xffff0000, v81
	v_fma_f32 v83, v96, v83, -v82
	v_exp_f32_e32 v86, v86
	v_fmac_f32_e32 v82, v11, v83
	v_add_f32_e32 v83, -1.0, v84
	v_fma_f32 v83, v27, v83, 1.0
	v_mul_f32_e32 v83, v137, v83
	v_mul_f32_e32 v137, v82, v91
	v_sub_f32_e32 v82, v214, v213
	v_mul_f32_e32 v194, v87, v85
	v_sub_f32_e32 v85, v216, v215
	v_mul_f32_e32 v215, v83, v86
	v_mul_f32_e32 v82, 0x3fb8aa3b, v82
	v_mul_f32_e32 v83, 0xbfb8aa3b, v214
	v_mul_f32_e32 v87, v190, v203
	v_lshlrev_b32_e32 v75, 16, v75
	v_lshlrev_b32_e32 v77, 16, v77
	v_exp_f32_e32 v82, v82
	v_exp_f32_e32 v83, v83
	v_mul_f32_e32 v84, v87, v84
	v_lshlrev_b32_e32 v81, 16, v81
	v_fma_f32 v77, v96, v77, -v75
	v_mul_f32_e32 v190, v84, v86
	v_fmac_f32_e32 v75, v10, v77
	v_add_f32_e32 v77, -1.0, v81
	v_mul_f32_e32 v84, v187, v203
	v_fma_f32 v77, v26, v77, 1.0
	v_mul_f32_e32 v81, v84, v81
	v_mul_f32_e32 v77, v136, v77
	v_mul_f32_e32 v91, v84, v82
	v_mul_f32_e32 v187, v81, v83
	v_mul_f32_e32 v136, v75, v212
	v_and_b32_e32 v75, 0xffff0000, v74
	v_and_b32_e32 v81, 0xffff0000, v76
	v_mul_f32_e32 v84, 0xbfb8aa3b, v211
	v_and_b32_e32 v82, 0xffff0000, v80
	v_fma_f32 v81, v96, v81, -v75
	v_exp_f32_e32 v84, v84
	v_mul_f32_e32 v85, 0x3fb8aa3b, v85
	v_fmac_f32_e32 v75, v9, v81
	v_add_f32_e32 v81, -1.0, v82
	v_exp_f32_e32 v85, v85
	v_fma_f32 v81, v25, v81, 1.0
	v_mul_f32_e32 v81, v139, v81
	v_mul_f32_e32 v77, v77, v83
	v_sub_f32_e32 v83, v211, v210
	v_mul_f32_e32 v210, v81, v84
	v_mul_f32_e32 v139, v75, v90
	v_lshlrev_b32_e32 v74, 16, v74
	v_lshlrev_b32_e32 v75, 16, v76
	v_lshlrev_b32_e32 v76, 16, v80
	v_sub_f32_e32 v80, v209, v208
	v_mul_f32_e32 v81, 0xbfb8aa3b, v209
	v_fma_f32 v75, v96, v75, -v74
	v_mul_f32_e32 v80, 0x3fb8aa3b, v80
	v_exp_f32_e32 v81, v81
	v_mul_f32_e32 v89, v87, v85
	v_mul_f32_e32 v85, v186, v203
	v_fmac_f32_e32 v74, v8, v75
	v_add_f32_e32 v75, -1.0, v76
	v_exp_f32_e32 v80, v80
	v_mul_f32_e32 v82, v85, v82
	v_fma_f32 v75, v24, v75, 1.0
	v_mul_f32_e32 v186, v82, v84
	v_mul_f32_e32 v75, v138, v75
	v_mul_f32_e32 v82, v184, v203
	v_mul_f32_e32 v83, 0x3fb8aa3b, v83
	v_mul_f32_e32 v76, v82, v76
	v_mul_f32_e32 v184, v75, v81
	v_mul_f32_e32 v138, v74, v207
	v_and_b32_e32 v74, 0xffff0000, v69
	v_and_b32_e32 v75, 0xffff0000, v71
	v_exp_f32_e32 v83, v83
	v_mul_f32_e32 v90, v82, v80
	v_mul_f32_e32 v76, v76, v81
	v_and_b32_e32 v80, 0xffff0000, v79
	v_fma_f32 v75, v96, v75, -v74
	v_sub_f32_e32 v81, v206, v205
	v_fmac_f32_e32 v74, v7, v75
	v_add_f32_e32 v75, -1.0, v80
	v_mul_f32_e32 v81, 0x3fb8aa3b, v81
	v_mul_f32_e32 v82, 0xbfb8aa3b, v206
	v_fma_f32 v75, v43, v75, 1.0
	v_exp_f32_e32 v81, v81
	v_exp_f32_e32 v82, v82
	v_mul_f32_e32 v75, v141, v75
	v_mul_f32_e32 v141, v74, v95
	v_lshlrev_b32_e32 v69, 16, v69
	v_lshlrev_b32_e32 v71, 16, v71
	v_lshlrev_b32_e32 v74, 16, v79
	v_mul_f32_e32 v79, 0xbfb8aa3b, v202
	v_mul_f32_e32 v88, v85, v83
	v_mul_f32_e32 v83, v181, v203
	v_fma_f32 v71, v96, v71, -v69
	v_exp_f32_e32 v79, v79
	v_mul_f32_e32 v80, v83, v80
	v_fmac_f32_e32 v69, v6, v71
	v_add_f32_e32 v71, -1.0, v74
	v_mul_f32_e32 v86, v83, v81
	v_mul_f32_e32 v83, v80, v82
	v_mul_f32_e32 v87, v75, v82
	v_fma_f32 v71, v42, v71, 1.0
	v_sub_f32_e32 v75, v202, v201
	v_mul_f32_e32 v80, v178, v203
	v_mul_f32_e32 v71, v140, v71
	v_mul_f32_e32 v75, 0x3fb8aa3b, v75
	v_mul_f32_e32 v74, v80, v74
	v_exp_f32_e32 v75, v75
	v_mul_f32_e32 v95, v74, v79
	v_mul_f32_e32 v178, v71, v79
	v_mul_f32_e32 v140, v69, v200
	v_and_b32_e32 v69, 0xffff0000, v68
	v_and_b32_e32 v71, 0xffff0000, v70
	v_mul_f32_e32 v79, 0xbfb8aa3b, v197
	v_and_b32_e32 v74, 0xffff0000, v78
	v_fma_f32 v71, v96, v71, -v69
	v_exp_f32_e32 v79, v79
	v_fmac_f32_e32 v69, v5, v71
	v_add_f32_e32 v71, -1.0, v74
	v_fma_f32 v71, v41, v71, 1.0
	v_mul_f32_e32 v82, v80, v75
	v_mul_f32_e32 v71, v176, v71
	v_sub_f32_e32 v75, v197, v196
	v_mul_f32_e32 v80, v177, v203
	v_mul_f32_e32 v75, 0x3fb8aa3b, v75
	v_mul_f32_e32 v74, v80, v74
	v_mul_f32_e32 v181, v71, v79
	v_sub_f32_e32 v71, v193, v192
	v_exp_f32_e32 v75, v75
	v_mul_f32_e32 v177, v74, v79
	v_mul_f32_e32 v79, v69, v94
	v_lshlrev_b32_e32 v68, 16, v68
	v_lshlrev_b32_e32 v69, 16, v70
	v_mul_f32_e32 v71, 0x3fb8aa3b, v71
	v_mul_f32_e32 v74, 0xbfb8aa3b, v193
	v_lshlrev_b32_e32 v70, 16, v78
	v_fma_f32 v69, v96, v69, -v68
	v_exp_f32_e32 v71, v71
	v_exp_f32_e32 v74, v74
	v_fmac_f32_e32 v68, v4, v69
	v_add_f32_e32 v69, -1.0, v70
	v_fma_f32 v69, v40, v69, 1.0
	v_mul_f32_e32 v176, v80, v75
	v_mul_f32_e32 v69, v149, v69
	v_mul_f32_e32 v75, v151, v203
	v_mul_f32_e32 v71, v75, v71
	v_mul_f32_e32 v70, v75, v70
	v_mul_f32_e32 v149, v69, v74
	v_mul_f32_e32 v78, v68, v191
	v_and_b32_e32 v68, 0xffff0000, v65
	v_and_b32_e32 v69, 0xffff0000, v67
	v_mul_f32_e32 v75, 0xbfb8aa3b, v189
	v_mul_f32_e32 v94, v70, v74
	v_and_b32_e32 v70, 0xffff0000, v73
	v_fma_f32 v69, v96, v69, -v68
	v_exp_f32_e32 v75, v75
	v_fmac_f32_e32 v68, v3, v69
	v_add_f32_e32 v69, -1.0, v70
	v_fma_f32 v69, v51, v69, 1.0
	v_sub_f32_e32 v74, v189, v188
	v_mul_f32_e32 v69, v143, v69
	v_mul_f32_e32 v74, 0x3fb8aa3b, v74
	v_mul_f32_e32 v80, v148, v203
	v_exp_f32_e32 v74, v74
	v_mul_f32_e32 v70, v80, v70
	v_mul_f32_e32 v85, v69, v75
	v_sub_f32_e32 v69, v185, v183
	v_mul_f32_e32 v70, v70, v75
	v_mul_f32_e32 v75, v68, v93
	v_lshlrev_b32_e32 v68, 16, v73
	v_mul_f32_e32 v69, 0x3fb8aa3b, v69
	v_mul_f32_e32 v73, 0xbfb8aa3b, v185
	v_lshlrev_b32_e32 v65, 16, v65
	v_lshlrev_b32_e32 v67, 16, v67
	v_exp_f32_e32 v69, v69
	v_exp_f32_e32 v73, v73
	v_fma_f32 v67, v96, v67, -v65
	v_mul_f32_e32 v81, v80, v74
	v_fmac_f32_e32 v65, v2, v67
	v_add_f32_e32 v67, -1.0, v68
	v_mul_f32_e32 v74, v142, v203
	v_fma_f32 v67, v50, v67, 1.0
	v_mul_f32_e32 v68, v74, v68
	v_mul_f32_e32 v67, v129, v67
	v_mul_f32_e32 v69, v74, v69
	v_mul_f32_e32 v84, v68, v73
	v_mul_f32_e32 v74, v65, v182
	v_and_b32_e32 v65, 0xffff0000, v64
	v_and_b32_e32 v68, 0xffff0000, v66
	v_mul_f32_e32 v67, v67, v73
	v_and_b32_e32 v73, 0xffff0000, v72
	v_fma_f32 v68, v96, v68, -v65
	v_mul_f32_e32 v93, 0xbfb8aa3b, v180
	v_fmac_f32_e32 v65, v1, v68
	v_add_f32_e32 v68, -1.0, v73
	v_exp_f32_e32 v93, v93
	v_fma_f32 v68, v49, v68, 1.0
	v_mul_f32_e32 v68, v125, v68
	v_sub_f32_e32 v80, v180, v179
	v_mul_f32_e32 v125, v127, v203
	v_mul_f32_e32 v143, v65, v92
	v_lshlrev_b32_e32 v65, 16, v72
	v_sub_f32_e32 v72, v175, v150
	v_mul_f32_e32 v80, 0x3fb8aa3b, v80
	v_mul_f32_e32 v73, v125, v73
	v_mul_f32_e32 v72, 0x3fb8aa3b, v72
	v_mul_f32_e32 v92, 0xbfb8aa3b, v175
	v_exp_f32_e32 v80, v80
	v_mul_f32_e32 v73, v73, v93
	v_mul_f32_e32 v93, v68, v93
	v_add_f32_e32 v68, -1.0, v65
	v_exp_f32_e32 v72, v72
	v_exp_f32_e32 v92, v92
	v_fma_f32 v68, v48, v68, 1.0
	v_mul_f32_e32 v68, v98, v68
	v_mul_f32_e32 v98, v99, v203
	v_mul_f32_e32 v65, v98, v65
	v_mul_f32_e32 v80, v125, v80
	v_mul_f32_e32 v72, v72, v98
	v_mul_f32_e32 v65, v92, v65
	v_mul_f32_e32 v92, v68, v92
	v_cvt_pk_bf16_f32 v68, v72, v80
	v_cvt_pk_bf16_f32 v69, v69, v81
	v_cvt_pk_bf16_f32 v80, v65, v73
	v_cvt_pk_bf16_f32 v81, v84, v70
	v_cvt_pk_bf16_f32 v70, v71, v176
	v_cvt_pk_bf16_f32 v71, v82, v86
	v_cvt_pk_bf16_f32 v82, v94, v177
	v_cvt_pk_bf16_f32 v83, v95, v83
	v_lshlrev_b32_e32 v72, 16, v64
	v_lshlrev_b32_e32 v64, 16, v66
	v_fma_f32 v73, v96, v64, -v72
	v_fmac_f32_e32 v72, v0, v73
	v_cvt_pk_bf16_f32 v84, v92, v93
	v_cvt_pk_bf16_f32 v92, v76, v186
	v_cvt_pk_bf16_f32 v93, v187, v190
	v_cvt_pk_bf16_f32 v94, v218, v195
	v_cvt_pk_bf16_f32 v95, v198, v199
	v_mul_f32_e32 v142, v72, v97
	v_cvt_pk_bf16_f32 v85, v67, v85
	v_cvt_pk_bf16_f32 v86, v149, v181
	v_cvt_pk_bf16_f32 v87, v178, v87
	v_cvt_pk_bf16_f32 v88, v90, v88
	v_cvt_pk_bf16_f32 v89, v91, v89
	v_cvt_pk_bf16_f32 v90, v194, v220
	v_cvt_pk_bf16_f32 v91, v204, v225
	v_mfma_f32_16x16x32_bf16 v[180:183], v[80:83], v[68:71], 0
	v_add_u32_e32 v72, 0x800, v155
	v_cvt_pk_bf16_f32 v96, v142, v143
	v_cvt_pk_bf16_f32 v97, v74, v75
	v_cvt_pk_bf16_f32 v98, v78, v79
	v_cvt_pk_bf16_f32 v99, v140, v141
	v_mfma_f32_16x16x32_bf16 v[176:179], v[68:71], v[84:87], 0
	ds_write2_b64 v155, v[68:69], v[70:71] offset1:4
	ds_write2_b64 v72, v[80:81], v[82:83] offset0:16 offset1:20
	v_add_u32_e32 v73, 0x1000, v155
	v_mfma_f32_16x16x32_bf16 v[68:71], v[68:71], v[80:83], 0
	v_cvt_pk_bf16_f32 v148, v184, v210
	v_cvt_pk_bf16_f32 v149, v77, v215
	v_cvt_pk_bf16_f32 v150, v219, v221
	v_mfma_f32_16x16x32_bf16 v[80:83], v[80:83], v[96:99], 0
	v_cvt_pk_bf16_f32 v151, v223, v226
	ds_write2_b64 v73, v[84:85], v[86:87] offset0:32 offset1:36
	ds_write2_b64 v155, v[88:89], v[90:91] offset0:8 offset1:12
	ds_write2_b64 v72, v[92:93], v[94:95] offset0:24 offset1:28
	ds_write2_b64 v73, v[148:149], v[150:151] offset0:40 offset1:44
	v_mfma_f32_16x16x32_bf16 v[64:67], v[92:95], v[88:91], v[180:183]
	s_waitcnt lgkmcnt(0)
	v_mov_b32_e32 v190, v103
	v_mov_b32_e32 v191, v103
	v_mfma_f32_16x16x32_bf16 v[68:71], v[88:91], v[92:95], v[68:71]
	v_cvt_pk_bf16_f32 v180, v138, v139
	v_cvt_pk_bf16_f32 v181, v136, v137
	v_cvt_pk_bf16_f32 v182, v134, v135
	v_cvt_pk_bf16_f32 v183, v130, v131
	v_mfma_f32_16x16x32_bf16 v[184:187], v[84:87], v[96:99], 0
	v_cndmask_b32_e64 v73, 0, -v64, s[6:7]
	s_nop 1
	v_cndmask_b32_e64 v68, 0, -v68, s[4:5]
	v_cndmask_b32_e64 v69, -v69, 0, s[6:7]
	v_mfma_f32_16x16x32_bf16 v[80:83], v[92:95], v[180:183], v[80:83]
	v_cndmask_b32_e64 v85, 0, -v66, s[14:15]
	v_cndmask_b32_e64 v70, 0, -v70, s[12:13]
	v_cndmask_b32_e64 v67, 0, -v67, s[18:19]
	v_cndmask_b32_e64 v92, 0, -v71, s[16:17]
	v_add_f32_e32 v64, v110, v68
	s_nop 2
	v_cndmask_b32_e64 v76, v80, 0, s[4:5]
	v_cndmask_b32_e64 v80, 0, -v65, s[8:9]
	v_add_f32_e32 v65, v111, v69
	v_add_f32_e32 v66, v112, v70
	v_cvt_pk_bf16_f32 v68, v68, v69
	v_cvt_pk_bf16_f32 v69, v70, v92
	v_mov_b32_e32 v70, v103
	v_mov_b32_e32 v71, v103
	v_cvt_pk_bf16_f32 v84, v73, v80
	v_cvt_pk_bf16_f32 v85, v85, v67
	v_mov_b32_e32 v86, v103
	v_mov_b32_e32 v87, v103
	v_mfma_f32_16x16x32_bf16 v[176:179], v[88:91], v[148:151], v[176:179]
	v_add_f32_e32 v67, v113, v92
	v_cvt_pk_bf16_f32 v92, v64, v65
	v_cvt_pk_bf16_f32 v93, v66, v67
	v_mfma_f32_16x16x32_bf16 v[88:91], v[68:71], v[84:87], 0
	v_mov_b32_e32 v94, v103
	v_mov_b32_e32 v95, v103
	v_cndmask_b32_e64 v73, 0, v81, s[6:7]
	v_mfma_f32_16x16x32_bf16 v[68:71], v[84:87], v[68:71], 0
	v_cndmask_b32_e64 v97, v82, 0, s[12:13]
	s_nop 2
	v_cvt_pk_bf16_f32 v84, v88, v89
	v_cvt_pk_bf16_f32 v85, v90, v91
	v_mov_b32_e32 v82, v103
	v_mfma_f32_16x16x32_bf16 v[184:187], v[148:151], v[180:183], v[184:187]
	v_cvt_pk_bf16_f32 v68, v68, v69
	v_cvt_pk_bf16_f32 v69, v70, v71
	v_mov_b32_e32 v70, v103
	v_mov_b32_e32 v71, v103
	v_mfma_f32_16x16x32_bf16 v[64:67], v[84:87], v[92:95], v[64:67]
	v_cndmask_b32_e64 v72, 0, v176, s[4:5]
	v_cndmask_b32_e64 v77, v177, 0, s[6:7]
	v_cndmask_b32_e64 v96, 0, v178, s[12:13]
	v_mfma_f32_16x16x32_bf16 v[88:91], v[68:71], v[84:87], 0
	v_cndmask_b32_e64 v129, v186, 0, s[12:13]
	s_nop 2
	v_cvt_pk_bf16_f32 v92, v64, v65
	v_cvt_pk_bf16_f32 v93, v66, v67
	v_mfma_f32_16x16x32_bf16 v[68:71], v[84:87], v[68:71], 0
	v_cndmask_b32_e64 v175, v187, 0, s[16:17]
	v_cvt_pk_bf16_f32 v84, v88, v89
	v_cvt_pk_bf16_f32 v85, v90, v91
	v_cndmask_b32_e64 v90, v83, 0, s[16:17]
	v_mov_b32_e32 v83, v103
	s_nop 2
	v_cvt_pk_bf16_f32 v68, v68, v69
	v_cvt_pk_bf16_f32 v69, v70, v71
	v_mov_b32_e32 v70, v103
	v_mov_b32_e32 v71, v103
	v_mfma_f32_16x16x32_bf16 v[64:67], v[84:87], v[92:95], v[64:67]
	v_cndmask_b32_e64 v89, 0, v179, s[16:17]
	v_cvt_pk_bf16_f32 v88, v72, v77
	v_cvt_pk_bf16_f32 v89, v96, v89
	v_mfma_f32_16x16x32_bf16 v[68:71], v[68:71], v[84:87], 0
	v_cndmask_b32_e64 v125, v184, 0, s[4:5]
	s_nop 2
	v_cvt_pk_bf16_f32 v80, v64, v65
	v_cvt_pk_bf16_f32 v81, v66, v67
	v_cndmask_b32_e64 v127, 0, v185, s[6:7]
	v_mov_b32_e32 v91, v103
	v_cvt_pk_bf16_f32 v68, v68, v69
	v_cvt_pk_bf16_f32 v69, v70, v71
	v_mov_b32_e32 v70, v103
	v_mov_b32_e32 v71, v103
	s_add_u32 s20, s35, s10
	s_addc_u32 s21, s42, s11
	v_mfma_f32_16x16x32_bf16 v[64:67], v[68:71], v[80:83], v[64:67]
	s_add_u32 s10, s20, 0x2800
	s_addc_u32 s11, s21, 0
	s_add_i32 s3, s43, s3
	s_nop 4
	v_cvt_pk_bf16_f32 v92, v64, v65
	v_cvt_pk_bf16_f32 v93, v66, v67
	v_cvt_pk_bf16_f32 v64, v76, v73
	v_cvt_pk_bf16_f32 v65, v97, v90
	v_mov_b32_e32 v66, v103
	v_mov_b32_e32 v67, v103
	v_mov_b32_e32 v90, v103
	s_cmpk_lt_i32 s3, 0x100
	v_mfma_f32_16x16x32_bf16 v[64:67], v[92:95], v[64:67], 0
	s_nop 7
	v_cvt_pk_bf16_f32 v84, v64, v65
	v_cvt_pk_bf16_f32 v85, v66, v67
	ds_read_u16 v64, v156
	ds_read_u16 v66, v156 offset:2176
	ds_read_u16 v67, v157
	ds_read_u16 v68, v157 offset:2176
	ds_read_u16 v65, v158
	ds_read_u16 v69, v158 offset:2176
	ds_read_u16 v70, v157 offset:4352
	ds_read_u16 v71, v159
	ds_read_u16 v72, v159 offset:2176
	ds_read_u16 v73, v160
	ds_read_u16 v76, v160 offset:2176
	ds_read_u16 v77, v161
	ds_read_u16 v182, v160 offset:4352
	ds_read_u16 v178, v159 offset:4352
	ds_read_u16 v179, v158 offset:4352
	s_waitcnt lgkmcnt(11)
	v_perm_b32 v96, v68, v66, s52
	v_add_u32_e32 v66, 0x1800, v154
	s_waitcnt lgkmcnt(7)
	v_perm_b32 v65, v71, v65, s52
	ds_read_u16 v71, v156 offset:4352
	v_perm_b32 v64, v67, v64, s52
	s_waitcnt lgkmcnt(7)
	v_perm_b32 v97, v72, v69, s52
	ds_read2_b32 v[150:151], v66 offset0:96 offset1:112
	ds_read_u16 v67, v161 offset:2176
	ds_read_u16 v68, v162
	ds_read_u16 v72, v162 offset:2176
	ds_read_u16 v69, v163
	ds_read_u16 v98, v163 offset:2176
	ds_read_u16 v183, v163 offset:4352
	ds_read_u16 v186, v162 offset:4352
	ds_read_u16 v187, v161 offset:4352
	s_waitcnt lgkmcnt(4)
	v_perm_b32 v69, v69, v68, s52
	v_perm_b32 v68, v77, v73, s52
	s_waitcnt lgkmcnt(3)
	v_perm_b32 v177, v98, v72, s52
	v_perm_b32 v176, v67, v76, s52
	ds_read_u16 v67, v164
	ds_read_u16 v76, v164 offset:2176
	ds_read_u16 v72, v165
	ds_read_u16 v77, v165 offset:2176
	ds_read_u16 v73, v166
	ds_read_u16 v98, v166 offset:2176
	ds_read_u16 v197, v165 offset:4352
	ds_read_u16 v99, v167
	ds_read_u16 v148, v167 offset:2176
	ds_read_u16 v184, v168
	ds_read_u16 v188, v168 offset:2176
	ds_read_u16 v185, v169
	ds_read_u16 v198, v168 offset:4352
	ds_read_u16 v199, v167 offset:4352
	ds_read_u16 v200, v166 offset:4352
	s_waitcnt lgkmcnt(7)
	v_perm_b32 v73, v99, v73, s52
	ds_read_u16 v201, v164 offset:4352
	v_perm_b32 v72, v72, v67, s52
	s_waitcnt lgkmcnt(7)
	v_perm_b32 v181, v148, v98, s52
	v_perm_b32 v180, v77, v76, s52
	ds_read2_b32 v[148:149], v66 offset0:128 offset1:144
	ds_read_u16 v66, v169 offset:2176
	ds_read_u16 v67, v170
	ds_read_u16 v98, v170 offset:2176
	ds_read_u16 v76, v171
	ds_read_u16 v99, v171 offset:2176
	ds_read_u16 v202, v171 offset:4352
	ds_read_u16 v203, v170 offset:4352
	ds_read_u16 v204, v169 offset:4352
	s_waitcnt lgkmcnt(4)
	v_perm_b32 v77, v76, v67, s52
	v_perm_b32 v76, v185, v184, s52
	s_waitcnt lgkmcnt(3)
	v_perm_b32 v185, v99, v98, s52
	v_mov_b32_e32 v98, v103
	v_mov_b32_e32 v99, v103
	v_perm_b32 v184, v66, v188, s52
	v_lshlrev_b32_e32 v67, 16, v70
	v_mfma_f32_16x16x32_bf16 v[96:99], v[92:95], v[96:99], 0
	v_lshlrev_b32_e32 v66, 16, v71
	v_lshlrev_b32_e32 v71, 16, v178
	v_lshlrev_b32_e32 v70, 16, v179
	v_mov_b32_e32 v178, v103
	v_mov_b32_e32 v179, v103
	s_nop 2
	v_cvt_pk_bf16_f32 v188, v96, v97
	v_cvt_pk_bf16_f32 v189, v98, v99
	v_mov_b32_e32 v196, v151
	v_mfma_f32_16x16x32_bf16 v[80:83], v[88:91], v[84:87], 0
	v_mfma_f32_16x16x32_bf16 v[96:99], v[88:91], v[188:191], 0
	s_nop 6
	v_sub_f32_e32 v129, v129, v82
	v_pk_add_f32 v[66:67], v[66:67], v[96:97] neg_lo:[0,1] neg_hi:[0,1]
	v_pk_add_f32 v[70:71], v[70:71], v[98:99] neg_lo:[0,1] neg_hi:[0,1]
	v_mfma_f32_16x16x32_bf16 v[96:99], v[92:95], v[176:179], 0
	v_mul_f32_e64 v66, v150, v66
	v_mul_f32_e64 v67, v150, v67
	v_pk_mul_f32 v[70:71], v[150:151], v[70:71] op_sel_hi:[0,1]
	v_cvt_pk_bf16_f32 v66, v66, v67
	v_cvt_pk_bf16_f32 v67, v70, v71
	v_lshl_add_u64 v[70:71], s[20:21], 0, v[104:105]
	s_nop 1
	v_cvt_pk_bf16_f32 v176, v96, v97
	v_cvt_pk_bf16_f32 v177, v98, v99
	v_add_co_u32_e32 v194, vcc, s53, v70
	s_nop 0
	v_mfma_f32_16x16x32_bf16 v[96:99], v[88:91], v[176:179], 0
	v_addc_co_u32_e32 v195, vcc, 0, v71, vcc
	v_lshl_add_u64 v[192:193], v[70:71], 0, s[36:37]
	global_store_dwordx2 v[194:195], v[66:67], off offset:-4096
	v_lshlrev_b32_e32 v67, 16, v187
	v_lshlrev_b32_e32 v66, 16, v182
	v_lshlrev_b32_e32 v71, 16, v183
	v_lshlrev_b32_e32 v70, 16, v186
	v_mov_b32_e32 v182, v103
	v_mov_b32_e32 v183, v103
	v_pk_add_f32 v[66:67], v[66:67], v[96:97] neg_lo:[0,1] neg_hi:[0,1]
	v_pk_add_f32 v[70:71], v[70:71], v[98:99] neg_lo:[0,1] neg_hi:[0,1]
	v_mfma_f32_16x16x32_bf16 v[96:99], v[92:95], v[180:183], 0
	v_mov_b32_e32 v186, v103
	v_mov_b32_e32 v187, v103
	v_pk_mul_f32 v[66:67], v[196:197], v[66:67] op_sel_hi:[0,1]
	v_pk_mul_f32 v[70:71], v[196:197], v[70:71] op_sel_hi:[0,1]
	v_mfma_f32_16x16x32_bf16 v[92:95], v[92:95], v[184:187], 0
	s_nop 2
	v_cvt_pk_bf16_f32 v96, v96, v97
	v_cvt_pk_bf16_f32 v97, v98, v99
	v_mov_b32_e32 v98, v103
	v_mov_b32_e32 v99, v103
	v_cvt_pk_bf16_f32 v66, v66, v67
	v_cvt_pk_bf16_f32 v67, v70, v71
	v_mfma_f32_16x16x32_bf16 v[180:183], v[88:91], v[96:99], 0
	global_store_dwordx2 v[192:193], v[66:67], off offset:512
	v_lshlrev_b32_e32 v67, 16, v197
	v_lshlrev_b32_e32 v66, 16, v201
	v_lshlrev_b32_e32 v71, 16, v199
	v_lshlrev_b32_e32 v70, 16, v200
	v_cvt_pk_bf16_f32 v92, v92, v93
	v_cvt_pk_bf16_f32 v93, v94, v95
	v_mov_b32_e32 v94, v103
	v_mov_b32_e32 v95, v103
	v_pk_add_f32 v[66:67], v[66:67], v[180:181] neg_lo:[0,1] neg_hi:[0,1]
	v_pk_add_f32 v[70:71], v[70:71], v[182:183] neg_lo:[0,1] neg_hi:[0,1]
	v_mfma_f32_16x16x32_bf16 v[88:91], v[88:91], v[92:95], 0
	v_mul_f32_e64 v66, v148, v66
	v_mul_f32_e64 v67, v148, v67
	v_pk_mul_f32 v[70:71], v[148:149], v[70:71] op_sel_hi:[0,1]
	v_cvt_pk_bf16_f32 v66, v66, v67
	v_cvt_pk_bf16_f32 v67, v70, v71
	global_store_dwordx2 v[192:193], v[66:67], off offset:1024
	s_waitcnt lgkmcnt(0)
	v_lshlrev_b32_e32 v67, 16, v204
	v_lshlrev_b32_e32 v66, 16, v198
	v_pk_add_f32 v[66:67], v[66:67], v[88:89] neg_lo:[0,1] neg_hi:[0,1]
	v_mov_b32_e32 v88, v149
	v_pk_mul_f32 v[70:71], v[88:89], v[66:67] op_sel_hi:[0,1]
	v_lshlrev_b32_e32 v67, 16, v202
	v_lshlrev_b32_e32 v66, 16, v203
	v_pk_add_f32 v[90:91], v[66:67], v[90:91] neg_lo:[0,1] neg_hi:[0,1]
	v_mov_b32_e32 v66, v103
	v_mov_b32_e32 v67, v103
	v_pk_mul_f32 v[90:91], v[88:89], v[90:91] op_sel_hi:[0,1]
	v_cvt_pk_bf16_f32 v70, v70, v71
	v_cvt_pk_bf16_f32 v71, v90, v91
	global_store_dwordx2 v[192:193], v[70:71], off offset:1536
	v_mov_b32_e32 v70, v103
	v_mov_b32_e32 v71, v103
	v_mfma_f32_16x16x32_bf16 v[180:183], v[64:67], v[84:87], 0
	v_sub_f32_e32 v89, v175, v83
	v_sub_f32_e32 v127, v127, v81
	v_sub_f32_e32 v125, v125, v80
	s_nop 4
	v_pk_add_f32 v[90:91], v[142:143], v[180:181] neg_lo:[0,1] neg_hi:[0,1]
	v_pk_add_f32 v[142:143], v[74:75], v[182:183] neg_lo:[0,1] neg_hi:[0,1]
	v_mfma_f32_16x16x32_bf16 v[180:183], v[68:71], v[84:87], 0
	v_mov_b32_e32 v74, v103
	v_mov_b32_e32 v75, v103
	v_cvt_pk_bf16_f32 v80, v90, v91
	v_cvt_pk_bf16_f32 v81, v142, v143
	v_mfma_f32_16x16x32_bf16 v[184:187], v[72:75], v[84:87], 0
	s_nop 2
	v_add_f32_e64 v180, v78, -v180
	v_add_f32_e64 v181, v79, -v181
	v_mov_b32_e32 v78, v103
	v_mov_b32_e32 v79, v103
	v_pk_add_f32 v[140:141], v[140:141], v[182:183] neg_lo:[0,1] neg_hi:[0,1]
	v_pk_add_f32 v[138:139], v[138:139], v[184:185] neg_lo:[0,1] neg_hi:[0,1]
	v_mfma_f32_16x16x32_bf16 v[84:87], v[76:79], v[84:87], 0
	v_add_f32_e64 v136, v136, -v186
	v_add_f32_e64 v137, v137, -v187
	v_cvt_pk_bf16_f32 v82, v180, v181
	v_cvt_pk_bf16_f32 v83, v140, v141
	s_nop 3
	v_pk_add_f32 v[84:85], v[134:135], v[84:85] neg_lo:[0,1] neg_hi:[0,1]
	v_pk_add_f32 v[86:87], v[130:131], v[86:87] neg_lo:[0,1] neg_hi:[0,1]
	v_lshl_add_u64 v[90:91], s[10:11], 0, v[106:107]
	global_store_dwordx4 v[90:91], v[80:83], off
	s_nop 1
	v_cvt_pk_bf16_f32 v80, v138, v139
	v_cvt_pk_bf16_f32 v81, v136, v137
	v_cvt_pk_bf16_f32 v82, v84, v85
	v_cvt_pk_bf16_f32 v83, v86, v87
	v_lshl_add_u64 v[84:85], s[10:11], 0, v[108:109]
	global_store_dwordx4 v[84:85], v[80:83], off
	s_nop 1
	v_cvt_pk_bf16_f32 v80, v125, v127
	v_cvt_pk_bf16_f32 v81, v129, v89
	global_store_dwordx2 v[194:195], v[80:81], off
	v_mfma_f32_16x16x32_bf16 v[80:83], v[64:67], v[188:191], 0
	s_nop 7
	v_pk_add_f32 v[80:81], v[110:111], v[80:81] neg_lo:[0,1] neg_hi:[0,1]
	s_nop 0
	v_pk_mul_f32 v[84:85], v[150:151], v[80:81] op_sel_hi:[0,1]
	v_pk_add_f32 v[80:81], v[112:113], v[82:83] neg_lo:[0,1] neg_hi:[0,1]
	s_nop 0
	v_pk_mul_f32 v[86:87], v[150:151], v[80:81] op_sel_hi:[0,1]
	v_mfma_f32_16x16x32_bf16 v[80:83], v[68:71], v[188:191], 0
	s_nop 7
	v_pk_add_f32 v[80:81], v[80:81], 0 op_sel_hi:[1,0] neg_lo:[1,0] neg_hi:[1,0]
	s_nop 0
	v_pk_mul_f32 v[90:91], v[150:151], v[80:81] op_sel_hi:[0,1]
	v_pk_add_f32 v[80:81], v[82:83], 0 op_sel_hi:[1,0] neg_lo:[1,0] neg_hi:[1,0]
	s_nop 0
	v_pk_mul_f32 v[130:131], v[150:151], v[80:81] op_sel_hi:[0,1]
	v_mfma_f32_16x16x32_bf16 v[80:83], v[72:75], v[188:191], 0
	s_nop 7
	v_pk_add_f32 v[80:81], v[80:81], 0 op_sel_hi:[1,0] neg_lo:[1,0] neg_hi:[1,0]
	s_nop 0
	v_pk_mul_f32 v[134:135], v[150:151], v[80:81] op_sel_hi:[0,1]
	v_pk_add_f32 v[80:81], v[82:83], 0 op_sel_hi:[1,0] neg_lo:[1,0] neg_hi:[1,0]
	s_nop 0
	v_pk_mul_f32 v[136:137], v[150:151], v[80:81] op_sel_hi:[0,1]
	v_mfma_f32_16x16x32_bf16 v[80:83], v[76:79], v[188:191], 0
	s_nop 7
	v_pk_add_f32 v[80:81], v[80:81], 0 op_sel_hi:[1,0] neg_lo:[1,0] neg_hi:[1,0]
	s_nop 0
	v_pk_mul_f32 v[138:139], v[150:151], v[80:81] op_sel_hi:[0,1]
	v_pk_add_f32 v[80:81], v[82:83], 0 op_sel_hi:[1,0] neg_lo:[1,0] neg_hi:[1,0]
	v_cvt_pk_bf16_f32 v82, v90, v91
	v_pk_mul_f32 v[140:141], v[150:151], v[80:81] op_sel_hi:[0,1]
	v_cvt_pk_bf16_f32 v80, v84, v85
	v_cvt_pk_bf16_f32 v81, v86, v87
	v_cvt_pk_bf16_f32 v83, v130, v131
	v_lshl_add_u64 v[84:85], s[20:21], 0, v[106:107]
	global_store_dwordx4 v[84:85], v[80:83], off
	s_nop 1
	v_cvt_pk_bf16_f32 v80, v134, v135
	v_cvt_pk_bf16_f32 v81, v136, v137
	v_cvt_pk_bf16_f32 v82, v138, v139
	v_cvt_pk_bf16_f32 v83, v140, v141
	global_store_dwordx4 v[84:85], v[80:83], off offset:1024
	s_nop 1
	v_mfma_f32_16x16x32_bf16 v[80:83], v[64:67], v[176:179], 0
	s_nop 7
	v_pk_add_f32 v[80:81], v[80:81], 0 op_sel_hi:[1,0] neg_lo:[1,0] neg_hi:[1,0]
	s_nop 0
	v_pk_mul_f32 v[86:87], v[196:197], v[80:81] op_sel_hi:[0,1]
	v_pk_add_f32 v[80:81], v[82:83], 0 op_sel_hi:[1,0] neg_lo:[1,0] neg_hi:[1,0]
	s_nop 0
	v_pk_mul_f32 v[90:91], v[196:197], v[80:81] op_sel_hi:[0,1]
	v_mfma_f32_16x16x32_bf16 v[80:83], v[68:71], v[176:179], 0
	s_nop 7
	v_pk_add_f32 v[80:81], v[114:115], v[80:81] neg_lo:[0,1] neg_hi:[0,1]
	s_nop 0
	v_pk_mul_f32 v[130:131], v[196:197], v[80:81] op_sel_hi:[0,1]
	v_pk_add_f32 v[80:81], v[116:117], v[82:83] neg_lo:[0,1] neg_hi:[0,1]
	s_nop 0
	v_pk_mul_f32 v[134:135], v[196:197], v[80:81] op_sel_hi:[0,1]
	v_mfma_f32_16x16x32_bf16 v[80:83], v[72:75], v[176:179], 0
	s_nop 7
	v_pk_add_f32 v[80:81], v[80:81], 0 op_sel_hi:[1,0] neg_lo:[1,0] neg_hi:[1,0]
	s_nop 0
	v_pk_mul_f32 v[136:137], v[196:197], v[80:81] op_sel_hi:[0,1]
	v_pk_add_f32 v[80:81], v[82:83], 0 op_sel_hi:[1,0] neg_lo:[1,0] neg_hi:[1,0]
	s_nop 0
	v_pk_mul_f32 v[138:139], v[196:197], v[80:81] op_sel_hi:[0,1]
	v_mfma_f32_16x16x32_bf16 v[80:83], v[76:79], v[176:179], 0
	s_nop 7
	v_pk_add_f32 v[80:81], v[80:81], 0 op_sel_hi:[1,0] neg_lo:[1,0] neg_hi:[1,0]
	s_nop 0
	v_pk_mul_f32 v[140:141], v[196:197], v[80:81] op_sel_hi:[0,1]
	v_pk_add_f32 v[80:81], v[82:83], 0 op_sel_hi:[1,0] neg_lo:[1,0] neg_hi:[1,0]
	v_cvt_pk_bf16_f32 v82, v130, v131
	v_pk_mul_f32 v[142:143], v[196:197], v[80:81] op_sel_hi:[0,1]
	v_cvt_pk_bf16_f32 v80, v86, v87
	v_cvt_pk_bf16_f32 v81, v90, v91
	v_cvt_pk_bf16_f32 v83, v134, v135
	global_store_dwordx4 v[84:85], v[80:83], off offset:2048
	s_nop 1
	v_cvt_pk_bf16_f32 v80, v136, v137
	v_cvt_pk_bf16_f32 v81, v138, v139
	v_cvt_pk_bf16_f32 v82, v140, v141
	v_cvt_pk_bf16_f32 v83, v142, v143
	global_store_dwordx4 v[84:85], v[80:83], off offset:3072
	v_add_co_u32_e32 v84, vcc, s28, v84
	s_nop 0
	v_mfma_f32_16x16x32_bf16 v[80:83], v[64:67], v[96:99], 0
	v_addc_co_u32_e32 v85, vcc, 0, v85, vcc
	v_mfma_f32_16x16x32_bf16 v[64:67], v[64:67], v[92:95], 0
	s_nop 5
	v_add_f32_e64 v80, -v80, 0
	v_add_f32_e64 v81, -v81, 0
	v_pk_add_f32 v[64:65], v[64:65], 0 op_sel_hi:[1,0] neg_lo:[1,0] neg_hi:[1,0]
	v_pk_mul_f32 v[86:87], v[148:149], v[80:81] op_sel_hi:[0,1]
	v_pk_add_f32 v[80:81], v[82:83], 0 op_sel_hi:[1,0] neg_lo:[1,0] neg_hi:[1,0]
	s_nop 0
	v_pk_mul_f32 v[90:91], v[148:149], v[80:81] op_sel_hi:[0,1]
	v_mfma_f32_16x16x32_bf16 v[80:83], v[68:71], v[96:99], 0
	s_nop 7
	v_pk_add_f32 v[80:81], v[80:81], 0 op_sel_hi:[1,0] neg_lo:[1,0] neg_hi:[1,0]
	s_nop 0
	v_pk_mul_f32 v[130:131], v[148:149], v[80:81] op_sel_hi:[0,1]
	v_pk_add_f32 v[80:81], v[82:83], 0 op_sel_hi:[1,0] neg_lo:[1,0] neg_hi:[1,0]
	s_nop 0
	v_pk_mul_f32 v[134:135], v[148:149], v[80:81] op_sel_hi:[0,1]
	v_mfma_f32_16x16x32_bf16 v[80:83], v[72:75], v[96:99], 0
	s_nop 7
	v_pk_add_f32 v[80:81], v[114:115], v[80:81] neg_lo:[0,1] neg_hi:[0,1]
	s_nop 0
	v_pk_mul_f32 v[136:137], v[148:149], v[80:81] op_sel_hi:[0,1]
	v_pk_add_f32 v[80:81], v[118:119], v[82:83] neg_lo:[0,1] neg_hi:[0,1]
	s_nop 0
	v_pk_mul_f32 v[138:139], v[148:149], v[80:81] op_sel_hi:[0,1]
	v_mfma_f32_16x16x32_bf16 v[80:83], v[76:79], v[96:99], 0
	s_nop 7
	v_pk_add_f32 v[80:81], v[80:81], 0 op_sel_hi:[1,0] neg_lo:[1,0] neg_hi:[1,0]
	s_nop 0
	v_pk_mul_f32 v[96:97], v[148:149], v[80:81] op_sel_hi:[0,1]
	v_pk_add_f32 v[80:81], v[82:83], 0 op_sel_hi:[1,0] neg_lo:[1,0] neg_hi:[1,0]
	v_cvt_pk_bf16_f32 v82, v130, v131
	v_pk_mul_f32 v[98:99], v[148:149], v[80:81] op_sel_hi:[0,1]
	v_cvt_pk_bf16_f32 v80, v86, v87
	v_cvt_pk_bf16_f32 v81, v90, v91
	v_cvt_pk_bf16_f32 v83, v134, v135
	global_store_dwordx4 v[84:85], v[80:83], off
	s_nop 1
	v_cvt_pk_bf16_f32 v80, v136, v137
	v_cvt_pk_bf16_f32 v81, v138, v139
	v_cvt_pk_bf16_f32 v82, v96, v97
	v_cvt_pk_bf16_f32 v83, v98, v99
	global_store_dwordx4 v[84:85], v[80:83], off offset:1024
	s_nop 1
	v_pk_mul_f32 v[80:81], v[88:89], v[64:65] op_sel_hi:[0,1]
	v_pk_add_f32 v[64:65], v[66:67], 0 op_sel_hi:[1,0] neg_lo:[1,0] neg_hi:[1,0]
	s_nop 0
	v_pk_mul_f32 v[82:83], v[88:89], v[64:65] op_sel_hi:[0,1]
	v_mfma_f32_16x16x32_bf16 v[64:67], v[68:71], v[92:95], 0
	s_nop 7
	v_pk_add_f32 v[64:65], v[64:65], 0 op_sel_hi:[1,0] neg_lo:[1,0] neg_hi:[1,0]
	s_nop 0
	v_pk_mul_f32 v[68:69], v[88:89], v[64:65] op_sel_hi:[0,1]
	v_pk_add_f32 v[64:65], v[66:67], 0 op_sel_hi:[1,0] neg_lo:[1,0] neg_hi:[1,0]
	s_nop 0
	v_pk_mul_f32 v[70:71], v[88:89], v[64:65] op_sel_hi:[0,1]
	v_mfma_f32_16x16x32_bf16 v[64:67], v[72:75], v[92:95], 0
	s_nop 7
	v_pk_add_f32 v[64:65], v[64:65], 0 op_sel_hi:[1,0] neg_lo:[1,0] neg_hi:[1,0]
	s_nop 0
	v_pk_mul_f32 v[72:73], v[88:89], v[64:65] op_sel_hi:[0,1]
	v_pk_add_f32 v[64:65], v[66:67], 0 op_sel_hi:[1,0] neg_lo:[1,0] neg_hi:[1,0]
	s_nop 0
	v_pk_mul_f32 v[74:75], v[88:89], v[64:65] op_sel_hi:[0,1]
	v_mfma_f32_16x16x32_bf16 v[64:67], v[76:79], v[92:95], 0
	s_nop 7
	v_pk_add_f32 v[64:65], v[114:115], v[64:65] neg_lo:[0,1] neg_hi:[0,1]
	s_nop 0
	v_pk_mul_f32 v[76:77], v[88:89], v[64:65] op_sel_hi:[0,1]
	v_pk_add_f32 v[64:65], v[120:121], v[66:67] neg_lo:[0,1] neg_hi:[0,1]
	v_cvt_pk_bf16_f32 v66, v68, v69
	v_pk_mul_f32 v[78:79], v[88:89], v[64:65] op_sel_hi:[0,1]
	v_cvt_pk_bf16_f32 v64, v80, v81
	v_cvt_pk_bf16_f32 v65, v82, v83
	v_cvt_pk_bf16_f32 v67, v70, v71
	global_store_dwordx4 v[84:85], v[64:67], off offset:2048
	s_nop 1
	v_cvt_pk_bf16_f32 v64, v72, v73
	v_cvt_pk_bf16_f32 v65, v74, v75
	v_cvt_pk_bf16_f32 v66, v76, v77
	v_cvt_pk_bf16_f32 v67, v78, v79
	global_store_dwordx4 v[84:85], v[64:67], off offset:3072
	s_waitcnt lgkmcnt(0)
	s_cbranch_scc0 .LBB0_837

.LBB0_1025:
	s_and_b64 vcc, exec, s[0:1]
	s_cbranch_vccz .LBB0_1045
	s_sub_i32 s3, s57, 4
	s_mul_i32 s15, s2, 0x3200
	s_add_u32 s4, s52, s15
	s_addc_u32 s5, s53, 0
	s_add_u32 s4, s4, 0x100000
	s_addc_u32 s5, s5, 0
	s_lshl_b32 s10, s3, 10
	s_add_u32 s4, s4, s10
	s_addc_u32 s5, s5, 0
	s_lshr_b32 s15, s2, 4
	s_mul_i32 s15, s15, 0x5400000
	s_and_b32 s20, s2, 15
	s_lshl_b32 s20, s20, 7
	s_add_u32 s15, s15, s20
	s_add_u32 s6, s52, s15
	s_addc_u32 s7, s53, 0
	s_add_u32 s6, s6, 0xdffd400
	s_addc_u32 s7, s7, 0
	v_lshlrev_b32_e32 v0, 4, v146
	s_cmp_eq_u32 s3, 0
	s_cbranch_scc1 .Lld_w0
	s_sub_i32 s15, s3, 1
	s_lshl_b32 s20, s15, 6
	v_add_u32_e32 v1, s20, v146
	v_lshrrev_b32_e32 v2, 3, v1
	v_and_b32_e32 v1, 7, v1
	v_mul_u32_u24_e32 v2, 0x5400, v2
	v_lshl_add_u32 v1, v1, 4, v2
	s_mov_b32 s8, 0x54000
	s_lshl_b32 s9, s15, 10
	s_add_u32 s9, s9, 0x3200
	s_mov_b64 s[12:13], -1
	s_cmp_eq_u32 s3, 3
	s_cselect_b32 s12, 0xff, s12
	s_cselect_b32 s13, 0, s13
	s_branch .Lld_wdone
.Lld_w0:
	v_lshlrev_b32_e32 v1, 4, v146
	s_add_u32 s6, s4, 0x3000
	s_addc_u32 s7, s5, 0
	s_mov_b32 s8, 0x64000
	s_mov_b32 s9, 0x3000
	s_mov_b32 s12, -1
	s_mov_b32 s13, 0
.Lld_wdone:
	s_lshl_b32 s15, s3, 6
	v_add_u32_e32 v6, s15, v146
	v_lshrrev_b32_e32 v7, 3, v6
	v_and_b32_e32 v6, 7, v6
	v_lshlrev_b32_e32 v3, 7, v7
	v_lshl_add_u32 v3, v6, 4, v3
	v_lshlrev_b32_e32 v5, 11, v7
	v_lshl_add_u32 v5, v6, 4, v5
	s_lshr_b32 s15, s2, 4
	s_lshl_b32 s15, s15, 23
	s_and_b32 s20, s2, 15
	s_lshl_b32 s20, s20, 7
	s_add_u32 s15, s15, s20
	s_add_u32 s68, s52, s15
	s_addc_u32 s69, s53, 0
	s_add_u32 s68, s68, 0x7ff8000
	s_addc_u32 s69, s69, 0
	s_cmp_ge_u32 s3, 2
	s_cselect_b32 s72, -1, 0
	s_cselect_b32 s73, -1, 0
	s_mov_b32 s15, 0
	s_and_b32 s22, s15, 3
	s_mul_i32 s22, s22, 29952
	s_lshl_b32 s20, s15, 1
	s_mul_i32 s23, s20, 0x64000
	s_add_u32 s28, s4, s23
	s_addc_u32 s29, s5, 0
	s_mul_i32 s23, s20, s8
	s_add_u32 s64, s6, s23
	s_addc_u32 s65, s7, 0
	s_add_u32 s26, s22, s10
	s_mov_b32 m0, s26
	s_nop 0
	global_load_lds_dwordx4 v0, s[28:29]
	s_add_u32 s28, s28, 0x1000
	s_addc_u32 s29, s29, 0
	s_add_i32 m0, s26, 0x1000
	s_nop 0
	global_load_lds_dwordx4 v0, s[28:29]
	s_add_u32 s28, s28, 0x1000
	s_addc_u32 s29, s29, 0
	s_add_i32 m0, s26, 0x2000
	s_nop 0
	global_load_lds_dwordx4 v0, s[28:29]
	s_add_i32 m0, s22, s9
	s_mov_b64 exec, s[12:13]
	global_load_lds_dwordx4 v1, s[64:65]
	s_mov_b64 exec, -1
	s_add_u32 s20, s20, 1
	s_add_u32 s22, s22, 14976
	s_mul_i32 s23, s20, 0x64000
	s_add_u32 s28, s4, s23
	s_addc_u32 s29, s5, 0
	s_mul_i32 s23, s20, s8
	s_add_u32 s64, s6, s23
	s_addc_u32 s65, s7, 0
	s_add_u32 s26, s22, s10
	s_mov_b32 m0, s26
	s_nop 0
	global_load_lds_dwordx4 v0, s[28:29]
	s_add_u32 s28, s28, 0x1000
	s_addc_u32 s29, s29, 0
	s_add_i32 m0, s26, 0x1000
	s_nop 0
	global_load_lds_dwordx4 v0, s[28:29]
	s_add_u32 s28, s28, 0x1000
	s_addc_u32 s29, s29, 0
	s_add_i32 m0, s26, 0x2000
	s_nop 0
	global_load_lds_dwordx4 v0, s[28:29]
	s_add_i32 m0, s22, s9
	s_mov_b64 exec, s[12:13]
	global_load_lds_dwordx4 v1, s[64:65]
	s_mov_b64 exec, -1
	s_mov_b32 s15, 1
	s_and_b32 s22, s15, 3
	s_mul_i32 s22, s22, 29952
	s_lshl_b32 s20, s15, 1
	s_mul_i32 s23, s20, 0x64000
	s_add_u32 s28, s4, s23
	s_addc_u32 s29, s5, 0
	s_mul_i32 s23, s20, s8
	s_add_u32 s64, s6, s23
	s_addc_u32 s65, s7, 0
	s_add_u32 s26, s22, s10
	s_mov_b32 m0, s26
	s_nop 0
	global_load_lds_dwordx4 v0, s[28:29]
	s_add_u32 s28, s28, 0x1000
	s_addc_u32 s29, s29, 0
	s_add_i32 m0, s26, 0x1000
	s_nop 0
	global_load_lds_dwordx4 v0, s[28:29]
	s_add_u32 s28, s28, 0x1000
	s_addc_u32 s29, s29, 0
	s_add_i32 m0, s26, 0x2000
	s_nop 0
	global_load_lds_dwordx4 v0, s[28:29]
	s_add_i32 m0, s22, s9
	s_mov_b64 exec, s[12:13]
	global_load_lds_dwordx4 v1, s[64:65]
	s_mov_b64 exec, -1
	s_add_u32 s20, s20, 1
	s_add_u32 s22, s22, 14976
	s_mul_i32 s23, s20, 0x64000
	s_add_u32 s28, s4, s23
	s_addc_u32 s29, s5, 0
	s_mul_i32 s23, s20, s8
	s_add_u32 s64, s6, s23
	s_addc_u32 s65, s7, 0
	s_add_u32 s26, s22, s10
	s_mov_b32 m0, s26
	s_nop 0
	global_load_lds_dwordx4 v0, s[28:29]
	s_add_u32 s28, s28, 0x1000
	s_addc_u32 s29, s29, 0
	s_add_i32 m0, s26, 0x1000
	s_nop 0
	global_load_lds_dwordx4 v0, s[28:29]
	s_add_u32 s28, s28, 0x1000
	s_addc_u32 s29, s29, 0
	s_add_i32 m0, s26, 0x2000
	s_nop 0
	global_load_lds_dwordx4 v0, s[28:29]
	s_add_i32 m0, s22, s9
	s_mov_b64 exec, s[12:13]
	global_load_lds_dwordx4 v1, s[64:65]
	s_mov_b64 exec, -1
	s_mov_b32 s15, 2
	s_and_b32 s22, s15, 3
	s_mul_i32 s22, s22, 29952
	s_lshl_b32 s20, s15, 1
	s_mul_i32 s23, s20, 0x64000
	s_add_u32 s28, s4, s23
	s_addc_u32 s29, s5, 0
	s_mul_i32 s23, s20, s8
	s_add_u32 s64, s6, s23
	s_addc_u32 s65, s7, 0
	s_add_u32 s26, s22, s10
	s_mov_b32 m0, s26
	s_nop 0
	global_load_lds_dwordx4 v0, s[28:29]
	s_add_u32 s28, s28, 0x1000
	s_addc_u32 s29, s29, 0
	s_add_i32 m0, s26, 0x1000
	s_nop 0
	global_load_lds_dwordx4 v0, s[28:29]
	s_add_u32 s28, s28, 0x1000
	s_addc_u32 s29, s29, 0
	s_add_i32 m0, s26, 0x2000
	s_nop 0
	global_load_lds_dwordx4 v0, s[28:29]
	s_add_i32 m0, s22, s9
	s_mov_b64 exec, s[12:13]
	global_load_lds_dwordx4 v1, s[64:65]
	s_mov_b64 exec, -1
	s_add_u32 s20, s20, 1
	s_add_u32 s22, s22, 14976
	s_mul_i32 s23, s20, 0x64000
	s_add_u32 s28, s4, s23
	s_addc_u32 s29, s5, 0
	s_mul_i32 s23, s20, s8
	s_add_u32 s64, s6, s23
	s_addc_u32 s65, s7, 0
	s_add_u32 s26, s22, s10
	s_mov_b32 m0, s26
	s_nop 0
	global_load_lds_dwordx4 v0, s[28:29]
	s_add_u32 s28, s28, 0x1000
	s_addc_u32 s29, s29, 0
	s_add_i32 m0, s26, 0x1000
	s_nop 0
	global_load_lds_dwordx4 v0, s[28:29]
	s_add_u32 s28, s28, 0x1000
	s_addc_u32 s29, s29, 0
	s_add_i32 m0, s26, 0x2000
	s_nop 0
	global_load_lds_dwordx4 v0, s[28:29]
	s_add_i32 m0, s22, s9
	s_mov_b64 exec, s[12:13]
	global_load_lds_dwordx4 v1, s[64:65]
	s_mov_b64 exec, -1
	s_waitcnt vmcnt(16)
	s_barrier
	s_mov_b32 s14, 0
.Lld_loop:
	s_add_u32 s15, s14, 3
	s_cmp_gt_u32 s15, 127
	s_cbranch_scc1 .Lld_tail
	s_and_b32 s22, s15, 3
	s_mul_i32 s22, s22, 29952
	s_lshl_b32 s20, s15, 1
	s_mul_i32 s23, s20, 0x64000
	s_add_u32 s28, s4, s23
	s_addc_u32 s29, s5, 0
	s_mul_i32 s23, s20, s8
	s_add_u32 s64, s6, s23
	s_addc_u32 s65, s7, 0
	s_add_u32 s26, s22, s10
	s_mov_b32 m0, s26
	s_nop 0
	global_load_lds_dwordx4 v0, s[28:29]
	s_add_u32 s28, s28, 0x1000
	s_addc_u32 s29, s29, 0
	s_add_i32 m0, s26, 0x1000
	s_nop 0
	global_load_lds_dwordx4 v0, s[28:29]
	s_add_u32 s28, s28, 0x1000
	s_addc_u32 s29, s29, 0
	s_add_i32 m0, s26, 0x2000
	s_nop 0
	global_load_lds_dwordx4 v0, s[28:29]
	s_add_i32 m0, s22, s9
	s_mov_b64 exec, s[12:13]
	global_load_lds_dwordx4 v1, s[64:65]
	s_mov_b64 exec, -1
	s_add_u32 s20, s20, 1
	s_add_u32 s22, s22, 14976
	s_mul_i32 s23, s20, 0x64000
	s_add_u32 s28, s4, s23
	s_addc_u32 s29, s5, 0
	s_mul_i32 s23, s20, s8
	s_add_u32 s64, s6, s23
	s_addc_u32 s65, s7, 0
	s_add_u32 s26, s22, s10
	s_mov_b32 m0, s26
	s_nop 0
	global_load_lds_dwordx4 v0, s[28:29]
	s_add_u32 s28, s28, 0x1000
	s_addc_u32 s29, s29, 0
	s_add_i32 m0, s26, 0x1000
	s_nop 0
	global_load_lds_dwordx4 v0, s[28:29]
	s_add_u32 s28, s28, 0x1000
	s_addc_u32 s29, s29, 0
	s_add_i32 m0, s26, 0x2000
	s_nop 0
	global_load_lds_dwordx4 v0, s[28:29]
	s_add_i32 m0, s22, s9
	s_mov_b64 exec, s[12:13]
	global_load_lds_dwordx4 v1, s[64:65]
	s_mov_b64 exec, -1
	s_waitcnt vmcnt(16)
	s_branch .Lld_bar
